# stick-breaking attention: P.V of the p1 half's key steps runs on a 2-deep V fragment ring while the p0 half's weights are computed in its MFMA gaps; p0 half's P.V follows
# baseline (speedup 1.0000x reference)
.Lstk_nm1:
	s_waitcnt lgkmcnt(3)
	v_mfma_f32_32x32x16_bf16 v[66:81], v[216:219], v[106:109], v[66:81]
	ds_read_b128 v[216:219], v173 offset:192
	v_exp_f32_e64 v200, -|v82|
	v_exp_f32_e64 v201, -|v83|
	v_exp_f32_e64 v202, -|v84|
	v_exp_f32_e64 v203, -|v85|
	v_pk_add_f32 v[200:201], v[200:201], v[236:237] op_sel_hi:[1,0]
	v_max_i32_e32 v174, 0, v82
	v_max_i32_e32 v175, 0, v83
	v_log_f32_e32 v200, v200
	v_log_f32_e32 v201, v201
	v_exp_f32_e64 v204, -|v86|
	v_exp_f32_e64 v205, -|v87|
	v_pk_add_f32 v[202:203], v[202:203], v[236:237] op_sel_hi:[1,0]
	s_waitcnt lgkmcnt(3)
	v_mfma_f32_32x32x16_bf16 v[66:81], v[220:223], v[110:113], v[66:81]
	ds_read_b128 v[220:223], v173 offset:224
	v_max_i32_e32 v176, 0, v84
	v_max_i32_e32 v177, 0, v85
	v_log_f32_e32 v202, v202
	v_log_f32_e32 v203, v203
	v_pk_add_f32 v[200:201], v[200:201], v[174:175]
	v_pk_add_f32 v[82:83], v[82:83], v[200:201] neg_lo:[0,1] neg_hi:[0,1]
	v_exp_f32_e64 v206, -|v88|
	v_exp_f32_e64 v207, -|v89|
	v_pk_add_f32 v[204:205], v[204:205], v[236:237] op_sel_hi:[1,0]
	v_max_i32_e32 v174, 0, v86
	v_max_i32_e32 v175, 0, v87
	v_log_f32_e32 v204, v204
	s_waitcnt lgkmcnt(3)
	v_mfma_f32_32x32x16_bf16 v[66:81], v[224:227], v[114:117], v[66:81]
	v_log_f32_e32 v205, v205
	v_pk_add_f32 v[202:203], v[202:203], v[176:177]
	v_pk_add_f32 v[84:85], v[84:85], v[202:203] neg_lo:[0,1] neg_hi:[0,1]
	v_exp_f32_e64 v208, -|v90|
	v_exp_f32_e64 v209, -|v91|
	v_pk_add_f32 v[206:207], v[206:207], v[236:237] op_sel_hi:[1,0]
	v_max_i32_e32 v176, 0, v88
	v_max_i32_e32 v177, 0, v89
	v_log_f32_e32 v206, v206
	v_log_f32_e32 v207, v207
	v_pk_add_f32 v[204:205], v[204:205], v[174:175]
	v_pk_add_f32 v[86:87], v[86:87], v[204:205] neg_lo:[0,1] neg_hi:[0,1]
	s_waitcnt lgkmcnt(2)
	v_mfma_f32_32x32x16_bf16 v[66:81], v[232:235], v[118:121], v[66:81]
	v_exp_f32_e64 v210, -|v92|
	v_exp_f32_e64 v211, -|v93|
	v_pk_add_f32 v[208:209], v[208:209], v[236:237] op_sel_hi:[1,0]
	v_max_i32_e32 v174, 0, v90
	v_max_i32_e32 v175, 0, v91
	v_log_f32_e32 v208, v208
	v_log_f32_e32 v209, v209
	v_pk_add_f32 v[206:207], v[206:207], v[176:177]
	v_pk_add_f32 v[88:89], v[88:89], v[206:207] neg_lo:[0,1] neg_hi:[0,1]
	v_exp_f32_e64 v212, -|v94|
	v_exp_f32_e64 v213, -|v95|
	v_pk_add_f32 v[210:211], v[210:211], v[236:237] op_sel_hi:[1,0]
	s_waitcnt lgkmcnt(1)
	v_mfma_f32_32x32x16_bf16 v[66:81], v[216:219], v[122:125], v[66:81]
	v_max_i32_e32 v176, 0, v92
	v_max_i32_e32 v177, 0, v93
	v_log_f32_e32 v210, v210
	v_log_f32_e32 v211, v211
	v_pk_add_f32 v[208:209], v[208:209], v[174:175]
	v_pk_add_f32 v[90:91], v[90:91], v[208:209] neg_lo:[0,1] neg_hi:[0,1]
	v_exp_f32_e64 v214, -|v96|
	v_exp_f32_e64 v215, -|v97|
	v_pk_add_f32 v[212:213], v[212:213], v[236:237] op_sel_hi:[1,0]
	v_max_i32_e32 v174, 0, v94
	v_max_i32_e32 v175, 0, v95
	v_log_f32_e32 v212, v212
	s_waitcnt lgkmcnt(0)
	v_mfma_f32_32x32x16_bf16 v[66:81], v[220:223], v[126:129], v[66:81]
	v_log_f32_e32 v213, v213
	v_pk_add_f32 v[210:211], v[210:211], v[176:177]
	v_pk_add_f32 v[92:93], v[92:93], v[210:211] neg_lo:[0,1] neg_hi:[0,1]
	v_pk_add_f32 v[214:215], v[214:215], v[236:237] op_sel_hi:[1,0]
	v_max_i32_e32 v176, 0, v96
	v_max_i32_e32 v177, 0, v97
	v_log_f32_e32 v214, v214
	v_log_f32_e32 v215, v215
	v_pk_add_f32 v[212:213], v[212:213], v[174:175]
	v_pk_add_f32 v[94:95], v[94:95], v[212:213] neg_lo:[0,1] neg_hi:[0,1]
	v_pk_add_f32 v[214:215], v[214:215], v[176:177]
	v_pk_add_f32 v[96:97], v[96:97], v[214:215] neg_lo:[0,1] neg_hi:[0,1]
	s_setprio 0
	v_cndmask_b32_e64 v173, 0, 1.0, s[4:5]
	v_pk_add_f32 v[174:175], v[200:201], v[202:203]
	v_add_f32_e32 v216, v174, v175
	v_mov_b32_e32 v220, v216
	v_pk_add_f32 v[176:177], v[204:205], v[206:207]
	v_add_f32_e32 v217, v176, v177
	v_mov_b32_e32 v221, v217
	v_pk_add_f32 v[174:175], v[208:209], v[210:211]
	v_add_f32_e32 v218, v174, v175
	v_mov_b32_e32 v222, v218
	v_pk_add_f32 v[176:177], v[212:213], v[214:215]
	v_add_f32_e32 v219, v176, v177
	v_mov_b32_e32 v223, v219
	s_nop 1
	v_permlane32_swap_b32_e32 v216, v220
	v_permlane32_swap_b32_e32 v217, v221
	v_permlane32_swap_b32_e32 v218, v222
	v_permlane32_swap_b32_e32 v219, v223
	v_add_f32_e32 v216, v216, v220
	v_add_f32_e32 v217, v217, v221
	v_add_f32_e32 v218, v218, v222
	v_add_f32_e32 v219, v219, v223
	v_fma_f32 v233, -v223, v173, v172
	v_sub_f32_e32 v232, v233, v215
	v_sub_f32_e32 v229, v232, v214
	v_sub_f32_e32 v228, v229, v213
	v_pk_add_f32 v[96:97], v[96:97], v[232:233]
	v_pk_add_f32 v[94:95], v[94:95], v[228:229]
	v_exp_f32_e32 v96, v96
	v_exp_f32_e32 v97, v97
	v_exp_f32_e32 v94, v94
	v_exp_f32_e32 v95, v95
	v_sub_f32_e32 v227, v172, v219
	v_fma_f32 v177, -v222, v173, v227
	v_sub_f32_e32 v176, v177, v211
	v_sub_f32_e32 v235, v176, v210
	v_sub_f32_e32 v234, v235, v209
	v_pk_add_f32 v[92:93], v[92:93], v[176:177]
	v_pk_add_f32 v[90:91], v[90:91], v[234:235]
	v_exp_f32_e32 v92, v92
	v_exp_f32_e32 v93, v93
	v_exp_f32_e32 v90, v90
	v_exp_f32_e32 v91, v91
	v_sub_f32_e32 v226, v227, v218
	v_fma_f32 v233, -v221, v173, v226
	v_sub_f32_e32 v232, v233, v207
	v_sub_f32_e32 v229, v232, v206
	v_sub_f32_e32 v228, v229, v205
	v_pk_add_f32 v[88:89], v[88:89], v[232:233]
	v_pk_add_f32 v[86:87], v[86:87], v[228:229]
	v_exp_f32_e32 v88, v88
	v_exp_f32_e32 v89, v89
	v_exp_f32_e32 v86, v86
	v_exp_f32_e32 v87, v87
	v_sub_f32_e32 v227, v226, v217
	v_fma_f32 v177, -v220, v173, v227
	v_sub_f32_e32 v182, v227, v216
	v_sub_f32_e32 v176, v177, v203
	v_sub_f32_e32 v235, v176, v202
	v_sub_f32_e32 v234, v235, v201
	v_pk_add_f32 v[84:85], v[84:85], v[176:177]
	v_pk_add_f32 v[82:83], v[82:83], v[234:235]
	v_exp_f32_e32 v84, v84
	v_exp_f32_e32 v85, v85
	v_exp_f32_e32 v82, v82
	v_exp_f32_e32 v83, v83
	v_add_u32_e32 v0, v0, v191
	v_cvt_pk_bf16_f32 v82, v82, v83
	v_cvt_pk_bf16_f32 v83, v84, v85
	v_cvt_pk_bf16_f32 v84, v86, v87
	v_cvt_pk_bf16_f32 v85, v88, v89
	v_cvt_pk_bf16_f32 v86, v90, v91
	v_cvt_pk_bf16_f32 v87, v92, v93
	v_cvt_pk_bf16_f32 v88, v94, v95
	v_cvt_pk_bf16_f32 v89, v96, v97
	ds_read_b128 v[90:93], v0 offset:17472
	ds_read_b128 v[94:97], v0 offset:22080
	s_setprio 1
	s_waitcnt lgkmcnt(1)
	v_mfma_f32_32x32x16_bf16 v[50:65], v[90:93], v[82:85], v[50:65]
	ds_read_b128 v[90:93], v0 offset:26688
	s_waitcnt lgkmcnt(1)
	v_mfma_f32_32x32x16_bf16 v[34:49], v[94:97], v[82:85], v[34:49]
	ds_read_b128 v[94:97], v0 offset:31296
	v_add_u32_e32 v199, 32, v159
	v_cmp_gt_i32_e32 vcc, 28, v199
	s_cmp_eq_u64 vcc, 0
	s_cbranch_scc1 .Lstk_nm0
	v_cmp_lt_i32_e64 s[0:1], 0, v199
	v_cmp_lt_i32_e64 s[8:9], 1, v199
	v_cmp_lt_i32_e64 s[10:11], 2, v199
	v_cmp_lt_i32_e64 s[12:13], 3, v199
	v_cndmask_b32_e64 v66, v231, v66, s[0:1]
	v_cndmask_b32_e64 v67, v231, v67, s[8:9]
	v_cndmask_b32_e64 v68, v231, v68, s[10:11]
	v_cndmask_b32_e64 v69, v231, v69, s[12:13]
	v_cmp_lt_i32_e64 s[0:1], 8, v199
	v_cmp_lt_i32_e64 s[8:9], 9, v199
	v_cmp_lt_i32_e64 s[10:11], 10, v199
	v_cmp_lt_i32_e64 s[12:13], 11, v199
	v_cndmask_b32_e64 v70, v231, v70, s[0:1]
	v_cndmask_b32_e64 v71, v231, v71, s[8:9]
	v_cndmask_b32_e64 v72, v231, v72, s[10:11]
	v_cndmask_b32_e64 v73, v231, v73, s[12:13]
	v_cmp_lt_i32_e64 s[0:1], 16, v199
	v_cmp_lt_i32_e64 s[8:9], 17, v199
	v_cmp_lt_i32_e64 s[10:11], 18, v199
	v_cmp_lt_i32_e64 s[12:13], 19, v199
	v_cndmask_b32_e64 v74, v231, v74, s[0:1]
	v_cndmask_b32_e64 v75, v231, v75, s[8:9]
	v_cndmask_b32_e64 v76, v231, v76, s[10:11]
	v_cndmask_b32_e64 v77, v231, v77, s[12:13]
	v_cmp_lt_i32_e64 s[0:1], 24, v199
	v_cmp_lt_i32_e64 s[8:9], 25, v199
	v_cmp_lt_i32_e64 s[10:11], 26, v199
	v_cmp_lt_i32_e64 s[12:13], 27, v199
	v_cndmask_b32_e64 v78, v231, v78, s[0:1]
	v_cndmask_b32_e64 v79, v231, v79, s[8:9]
	v_cndmask_b32_e64 v80, v231, v80, s[10:11]
	v_cndmask_b32_e64 v81, v231, v81, s[12:13]
.Lstk_nm0:
	s_waitcnt lgkmcnt(1)
	v_mfma_f32_32x32x16_bf16 v[18:33], v[90:93], v[82:85], v[18:33]
	ds_read_b128 v[90:93], v0 offset:17504
	v_exp_f32_e64 v200, -|v66|
	v_exp_f32_e64 v201, -|v67|
	v_exp_f32_e64 v202, -|v68|
	v_exp_f32_e64 v203, -|v69|
	v_pk_add_f32 v[200:201], v[200:201], v[236:237] op_sel_hi:[1,0]
	v_max_i32_e32 v174, 0, v66
	v_max_i32_e32 v175, 0, v67
	v_log_f32_e32 v200, v200
	v_log_f32_e32 v201, v201
	v_exp_f32_e64 v204, -|v70|
	v_exp_f32_e64 v205, -|v71|
	v_pk_add_f32 v[202:203], v[202:203], v[236:237] op_sel_hi:[1,0]
	v_max_i32_e32 v176, 0, v68
	v_max_i32_e32 v177, 0, v69
	v_log_f32_e32 v202, v202
	v_log_f32_e32 v203, v203
	v_pk_add_f32 v[200:201], v[200:201], v[174:175]
	v_pk_add_f32 v[66:67], v[66:67], v[200:201] neg_lo:[0,1] neg_hi:[0,1]
	v_exp_f32_e64 v206, -|v72|
	v_exp_f32_e64 v207, -|v73|
	v_pk_add_f32 v[204:205], v[204:205], v[236:237] op_sel_hi:[1,0]
	v_max_i32_e32 v174, 0, v70
	v_max_i32_e32 v175, 0, v71
	s_waitcnt lgkmcnt(1)
	v_mfma_f32_32x32x16_bf16 v[2:17], v[94:97], v[82:85], v[2:17]
	ds_read_b128 v[94:97], v0 offset:22112
	v_log_f32_e32 v204, v204
	v_log_f32_e32 v205, v205
	v_pk_add_f32 v[202:203], v[202:203], v[176:177]
	v_pk_add_f32 v[68:69], v[68:69], v[202:203] neg_lo:[0,1] neg_hi:[0,1]
	v_exp_f32_e64 v208, -|v74|
	v_exp_f32_e64 v209, -|v75|
	v_pk_add_f32 v[206:207], v[206:207], v[236:237] op_sel_hi:[1,0]
	v_max_i32_e32 v176, 0, v72
	v_max_i32_e32 v177, 0, v73
	v_log_f32_e32 v206, v206
	v_log_f32_e32 v207, v207
	v_pk_add_f32 v[204:205], v[204:205], v[174:175]
	v_pk_add_f32 v[70:71], v[70:71], v[204:205] neg_lo:[0,1] neg_hi:[0,1]
	v_exp_f32_e64 v210, -|v76|
	v_exp_f32_e64 v211, -|v77|
	v_pk_add_f32 v[208:209], v[208:209], v[236:237] op_sel_hi:[1,0]
	v_max_i32_e32 v174, 0, v74
	v_max_i32_e32 v175, 0, v75
	v_log_f32_e32 v208, v208
	v_log_f32_e32 v209, v209
	v_pk_add_f32 v[206:207], v[206:207], v[176:177]
	v_pk_add_f32 v[72:73], v[72:73], v[206:207] neg_lo:[0,1] neg_hi:[0,1]
	v_exp_f32_e64 v212, -|v78|
	s_waitcnt lgkmcnt(1)
	v_mfma_f32_32x32x16_bf16 v[50:65], v[90:93], v[86:89], v[50:65]
	ds_read_b128 v[90:93], v0 offset:26720
	v_exp_f32_e64 v213, -|v79|
	v_pk_add_f32 v[210:211], v[210:211], v[236:237] op_sel_hi:[1,0]
	v_max_i32_e32 v176, 0, v76
	v_max_i32_e32 v177, 0, v77
	v_log_f32_e32 v210, v210
	v_log_f32_e32 v211, v211
	v_pk_add_f32 v[208:209], v[208:209], v[174:175]
	v_pk_add_f32 v[74:75], v[74:75], v[208:209] neg_lo:[0,1] neg_hi:[0,1]
	v_exp_f32_e64 v214, -|v80|
	v_exp_f32_e64 v215, -|v81|
	v_pk_add_f32 v[212:213], v[212:213], v[236:237] op_sel_hi:[1,0]
	v_max_i32_e32 v174, 0, v78
	v_max_i32_e32 v175, 0, v79
	v_log_f32_e32 v212, v212
	v_log_f32_e32 v213, v213
	v_pk_add_f32 v[210:211], v[210:211], v[176:177]
	v_pk_add_f32 v[76:77], v[76:77], v[210:211] neg_lo:[0,1] neg_hi:[0,1]
	v_pk_add_f32 v[214:215], v[214:215], v[236:237] op_sel_hi:[1,0]
	v_max_i32_e32 v176, 0, v80
	v_max_i32_e32 v177, 0, v81
	v_log_f32_e32 v214, v214
	v_log_f32_e32 v215, v215
	v_pk_add_f32 v[212:213], v[212:213], v[174:175]
	s_waitcnt lgkmcnt(1)
	v_mfma_f32_32x32x16_bf16 v[34:49], v[94:97], v[86:89], v[34:49]
	ds_read_b128 v[94:97], v0 offset:31328
	v_pk_add_f32 v[78:79], v[78:79], v[212:213] neg_lo:[0,1] neg_hi:[0,1]
	v_pk_add_f32 v[214:215], v[214:215], v[176:177]
	v_pk_add_f32 v[80:81], v[80:81], v[214:215] neg_lo:[0,1] neg_hi:[0,1]
	v_pk_add_f32 v[174:175], v[200:201], v[202:203]
	v_add_f32_e32 v216, v174, v175
	v_mov_b32_e32 v220, v216
	v_pk_add_f32 v[176:177], v[204:205], v[206:207]
	v_add_f32_e32 v217, v176, v177
	v_mov_b32_e32 v221, v217
	v_pk_add_f32 v[174:175], v[208:209], v[210:211]
	v_add_f32_e32 v218, v174, v175
	v_mov_b32_e32 v222, v218
	v_pk_add_f32 v[176:177], v[212:213], v[214:215]
	v_add_f32_e32 v219, v176, v177
	v_mov_b32_e32 v223, v219
	s_nop 1
	v_permlane32_swap_b32_e32 v216, v220
	v_permlane32_swap_b32_e32 v217, v221
	v_permlane32_swap_b32_e32 v218, v222
	v_permlane32_swap_b32_e32 v219, v223
	v_add_f32_e32 v216, v216, v220
	v_add_f32_e32 v217, v217, v221
	v_add_f32_e32 v218, v218, v222
	s_waitcnt lgkmcnt(1)
	v_mfma_f32_32x32x16_bf16 v[18:33], v[90:93], v[86:89], v[18:33]
	v_add_f32_e32 v219, v219, v223
	v_fma_f32 v233, -v223, v173, v182
	v_sub_f32_e32 v232, v233, v215
	v_sub_f32_e32 v229, v232, v214
	v_sub_f32_e32 v228, v229, v213
	v_pk_add_f32 v[80:81], v[80:81], v[232:233]
	v_pk_add_f32 v[78:79], v[78:79], v[228:229]
	v_exp_f32_e32 v80, v80
	v_exp_f32_e32 v81, v81
	v_exp_f32_e32 v78, v78
	v_exp_f32_e32 v79, v79
	v_sub_f32_e32 v227, v182, v219
	v_fma_f32 v177, -v222, v173, v227
	v_sub_f32_e32 v176, v177, v211
	v_sub_f32_e32 v235, v176, v210
	v_sub_f32_e32 v234, v235, v209
	v_pk_add_f32 v[76:77], v[76:77], v[176:177]
	v_pk_add_f32 v[74:75], v[74:75], v[234:235]
	v_exp_f32_e32 v76, v76
	v_exp_f32_e32 v77, v77
	v_exp_f32_e32 v74, v74
	v_exp_f32_e32 v75, v75
	v_sub_f32_e32 v226, v227, v218
	s_waitcnt lgkmcnt(0)
	v_mfma_f32_32x32x16_bf16 v[2:17], v[94:97], v[86:89], v[2:17]
	v_fma_f32 v233, -v221, v173, v226
	v_sub_f32_e32 v232, v233, v207
	v_sub_f32_e32 v229, v232, v206
	v_sub_f32_e32 v228, v229, v205
	v_pk_add_f32 v[72:73], v[72:73], v[232:233]
	v_pk_add_f32 v[70:71], v[70:71], v[228:229]
	v_exp_f32_e32 v72, v72
	v_exp_f32_e32 v73, v73
	v_exp_f32_e32 v70, v70
	v_exp_f32_e32 v71, v71
	v_sub_f32_e32 v227, v226, v217
	v_fma_f32 v177, -v220, v173, v227
	v_sub_f32_e32 v230, v227, v216
	v_sub_f32_e32 v176, v177, v203
	v_sub_f32_e32 v235, v176, v202
	v_sub_f32_e32 v234, v235, v201
	v_pk_add_f32 v[68:69], v[68:69], v[176:177]
	v_pk_add_f32 v[66:67], v[66:67], v[234:235]
	v_exp_f32_e32 v68, v68
	v_exp_f32_e32 v69, v69
	v_exp_f32_e32 v66, v66
	v_exp_f32_e32 v67, v67
	s_setprio 0
	v_sub_f32_e32 v173, v230, v172
	v_cvt_pk_bf16_f32 v66, v66, v67
	v_cvt_pk_bf16_f32 v67, v68, v69
	v_cvt_pk_bf16_f32 v68, v70, v71
	v_cvt_pk_bf16_f32 v69, v72, v73
	v_cvt_pk_bf16_f32 v70, v74, v75
	v_cvt_pk_bf16_f32 v71, v76, v77
	v_cvt_pk_bf16_f32 v72, v78, v79
	v_cvt_pk_bf16_f32 v73, v80, v81
	ds_read_b128 v[74:77], v0 offset:17408
	ds_read_b128 v[78:81], v0 offset:22016
	ds_read_b128 v[90:93], v0 offset:26624
	ds_read_b128 v[94:97], v0 offset:31232
	ds_read_b128 v[200:203], v0 offset:17440
	ds_read_b128 v[204:207], v0 offset:22048
	ds_read_b128 v[208:211], v0 offset:26656
	ds_read_b128 v[212:215], v0 offset:31264
	s_setprio 1
	s_waitcnt lgkmcnt(7)
	v_mfma_f32_32x32x16_bf16 v[50:65], v[74:77], v[66:69], v[50:65]
	s_waitcnt lgkmcnt(6)
	v_mfma_f32_32x32x16_bf16 v[34:49], v[78:81], v[66:69], v[34:49]
	s_waitcnt lgkmcnt(5)
	v_mfma_f32_32x32x16_bf16 v[18:33], v[90:93], v[66:69], v[18:33]
	s_waitcnt lgkmcnt(4)
	v_mfma_f32_32x32x16_bf16 v[2:17], v[94:97], v[66:69], v[2:17]
	s_waitcnt lgkmcnt(3)
	v_mfma_f32_32x32x16_bf16 v[50:65], v[200:203], v[70:73], v[50:65]
	s_waitcnt lgkmcnt(2)
	v_mfma_f32_32x32x16_bf16 v[34:49], v[204:207], v[70:73], v[34:49]
	s_waitcnt lgkmcnt(1)
	v_mfma_f32_32x32x16_bf16 v[18:33], v[208:211], v[70:73], v[18:33]
	s_waitcnt lgkmcnt(0)
	v_mfma_f32_32x32x16_bf16 v[2:17], v[212:215], v[70:73], v[2:17]
	s_setprio 0
	v_add_f32_e32 v172, v172, v173
